# v7_p1_bound
# baseline (speedup 1.0000x reference)
; __global__ void __launch_bounds__(512, 2) fwd_megakernel(Params p) {
;     ...
;     for (int ph2 = p.ph_lo * 2; ph2 < p.ph_hi * 2; ++ph2) {
;         const int ph = ph2 >> 1;
;         if ((ph2 & 1) && !((DUP_MASK >> ph) & 1)) continue;
;     ...
;         if (p.coop && ph2 + 1 < p.ph_hi * 2) grid.sync();
.LBB0_908:
	s_add_i32 s0, s87, 2
	v_readlane_b32 s12, v255, 2
	s_cmp_lt_i32 s0, s12
	v_readlane_b32 s4, v253, 29
	s_cselect_b64 s[0:1], -1, 0
	v_readlane_b32 s5, v253, 30
	s_and_b64 s[0:1], s[4:5], s[0:1]
	s_andn2_b64 vcc, exec, s[0:1]
	v_readlane_b32 s6, v254, 60
	v_readlane_b32 s8, v254, 62
	v_readlane_b32 s7, v254, 61
	v_readlane_b32 s9, v254, 63
	s_cbranch_vccnz .LBB0_4
	s_waitcnt vmcnt(0)
	s_barrier
	s_mov_b64 s[0:1], exec
	v_readlane_b32 s4, v254, 10
	v_readlane_b32 s5, v254, 11
	s_and_b64 s[4:5], s[0:1], s[4:5]
	s_mov_b64 exec, s[4:5]
	s_cbranch_execz .LBB0_3
	s_cmp_lg_u32 s99, 0
	s_cbranch_scc1 .Lfast_bar
	v_readlane_b32 s6, v255, 3
	s_lshl_b32 s7, s6, 8
	v_mov_b32_e32 v1, s7
	global_atomic_and v2, v1, v0, s[100:101] offset:2048 sc0
	s_cmp_lg_u32 s6, 0
	s_cbranch_scc1 .Lfast_init_done
	global_atomic_and v2, v0, v0, s[100:101] sc0

; __global__ void __launch_bounds__(512, 2) fwd_megakernel(Params p) {
;     ...
;         if (p.coop && ph2 + 1 < p.ph_hi * 2) grid.sync();
.Lfast_poll_loop:
	global_load_dword v2, v1, s[100:101] offset:2048 sc1
	s_waitcnt vmcnt(0)
	v_readfirstlane_b32 s6, v2
	s_cmp_ge_u32 s6, s99
	s_cbranch_scc1 .LBB0_2
	s_sleep 1
	s_add_u32 s98, s98, 1
	s_cmp_lt_u32 s98, 0x400000
	s_cbranch_scc1 .Lfast_poll_loop
	s_branch .LBB0_2
